# GLA chunk MFMA stage rescheduled: all LDS reads hoisted (offset regs compacted to free 26 VGPRs), state-update MFMAs fill the A^T latency/mask window, same accumulation order
# baseline (speedup 1.0000x reference)
.LBB0_533:
	s_or_b64 exec, exec, s[10:11]
	v_cmp_gt_i32_e32 vcc, 64, v2
	v_lshlrev_b32_e32 v129, 2, v2
	s_and_saveexec_b64 s[10:11], vcc
	ds_write_b32 v129, v179 offset:23552
	s_or_b64 exec, exec, s[10:11]
	s_add_u32 s58, s2, 0x22622100
	s_addc_u32 s59, s3, 0
	s_ashr_i32 s54, s95, 2
	v_lshlrev_b32_e32 v25, 3, v8
	s_add_u32 s56, s2, 0x18e80000
	v_and_b32_e32 v3, 24, v25
	s_addc_u32 s57, s3, 0
	s_ashr_i32 s55, s54, 31
	v_mul_u32_u24_e32 v3, 0x480, v3
	s_mul_i32 s10, s54, 0x480000
	v_add3_u32 v178, v0, s5, v3
	s_mul_hi_i32 s5, s54, 0x480000
	s_add_u32 s12, s58, s10
	s_addc_u32 s13, s59, s5
	v_lshl_add_u64 v[4:5], v[178:179], 1, s[12:13]
	v_add_u32_e32 v72, 0xc0, v178
	v_mov_b32_e32 v73, v179
	v_add_u32_e32 v74, 0x480, v178
	v_mov_b32_e32 v75, v179
	v_add_u32_e32 v76, 0x540, v178
	v_mov_b32_e32 v77, v179
	v_add_u32_e32 v78, 0x900, v178
	v_mov_b32_e32 v79, v179
	v_add_u32_e32 v80, 0x9c0, v178
	v_mov_b32_e32 v81, v179
	v_add_u32_e32 v82, 0xd80, v178
	v_mov_b32_e32 v83, v179
	v_add_u32_e32 v84, 0xe40, v178
	v_mov_b32_e32 v85, v179
	v_add_u32_e32 v86, 0x1200, v178
	v_mov_b32_e32 v87, v179
	v_mul_hi_u32 v3, v2, s87
	v_lshl_add_u64 v[6:7], v[72:73], 1, s[12:13]
	v_lshl_add_u64 v[12:13], v[74:75], 1, s[12:13]
	v_lshl_add_u64 v[14:15], v[76:77], 1, s[12:13]
	v_lshl_add_u64 v[16:17], v[78:79], 1, s[12:13]
	v_lshl_add_u64 v[18:19], v[80:81], 1, s[12:13]
	v_lshl_add_u64 v[20:21], v[82:83], 1, s[12:13]
	v_lshl_add_u64 v[22:23], v[84:85], 1, s[12:13]
	global_load_ushort v26, v[4:5], off
	global_load_ushort v143, v[6:7], off
	global_load_ushort v27, v[12:13], off
	global_load_ushort v140, v[14:15], off
	global_load_ushort v28, v[16:17], off
	global_load_ushort v136, v[18:19], off
	global_load_ushort v29, v[20:21], off
	global_load_ushort v138, v[22:23], off
	v_lshl_add_u64 v[4:5], v[86:87], 1, s[12:13]
	v_add_u32_e32 v88, 0x12c0, v178
	v_mov_b32_e32 v89, v179
	v_add_u32_e32 v90, 0x1680, v178
	v_mov_b32_e32 v91, v179
	v_add_u32_e32 v92, 0x1740, v178
	v_mov_b32_e32 v93, v179
	v_add_u32_e32 v94, 0x1b00, v178
	v_mov_b32_e32 v95, v179
	v_add_u32_e32 v96, 0x1bc0, v178
	v_mov_b32_e32 v97, v179
	v_add_u32_e32 v98, 0x1f80, v178
	v_mov_b32_e32 v99, v179
	v_add_u32_e32 v100, 0x2040, v178
	v_mov_b32_e32 v101, v179
	v_lshrrev_b32_e32 v3, 6, v3
	v_lshl_add_u64 v[6:7], v[88:89], 1, s[12:13]
	v_lshl_add_u64 v[12:13], v[90:91], 1, s[12:13]
	v_lshl_add_u64 v[14:15], v[92:93], 1, s[12:13]
	v_lshl_add_u64 v[16:17], v[94:95], 1, s[12:13]
	v_lshl_add_u64 v[18:19], v[96:97], 1, s[12:13]
	v_lshl_add_u64 v[20:21], v[98:99], 1, s[12:13]
	v_lshl_add_u64 v[22:23], v[100:101], 1, s[12:13]
	global_load_ushort v30, v[4:5], off
	global_load_ushort v144, v[6:7], off
	global_load_ushort v31, v[12:13], off
	global_load_ushort v142, v[14:15], off
	global_load_ushort v32, v[16:17], off
	global_load_ushort v137, v[18:19], off
	global_load_ushort v33, v[20:21], off
	global_load_ushort v139, v[22:23], off
	s_mul_i32 s5, s4, 0x60
	v_mul_lo_u32 v4, v3, s86
	v_mul_lo_u32 v3, v3, s75
	s_addk_i32 s5, 0x180
	v_sub_u32_e32 v3, v2, v3
	v_add_u32_e32 v34, 0x100, v2
	v_add3_u32 v102, v3, s5, v4
	v_mul_hi_u32 v3, v34, s87
	v_lshrrev_b32_e32 v3, 6, v3
	v_mul_lo_u32 v6, v3, s86
	v_mul_lo_u32 v3, v3, s75
	v_sub_u32_e32 v3, v34, v3
	v_add_u32_e32 v35, 0x200, v2
	v_add3_u32 v104, v3, s5, v6
	v_mul_hi_u32 v3, v35, s87
	v_lshrrev_b32_e32 v3, 6, v3
	v_mul_lo_u32 v12, v3, s86
	v_mul_lo_u32 v3, v3, s75
	v_sub_u32_e32 v3, v35, v3
	v_add_u32_e32 v36, 0x300, v2
	v_add3_u32 v106, v3, s5, v12
	v_mul_hi_u32 v3, v36, s87
	v_lshrrev_b32_e32 v3, 6, v3
	v_mul_lo_u32 v14, v3, s86
	v_mul_lo_u32 v3, v3, s75
	v_sub_u32_e32 v3, v36, v3
	v_add_u32_e32 v37, 0x400, v2
	v_add3_u32 v108, v3, s5, v14
	v_mul_hi_u32 v3, v37, s87
	v_lshrrev_b32_e32 v3, 6, v3
	v_mul_lo_u32 v16, v3, s86
	v_mul_lo_u32 v3, v3, s75
	v_sub_u32_e32 v3, v37, v3
	v_add_u32_e32 v38, 0x500, v2
	v_add3_u32 v110, v3, s5, v16
	v_mul_hi_u32 v3, v38, s87
	v_lshrrev_b32_e32 v3, 6, v3
	v_mul_lo_u32 v18, v3, s86
	v_mul_lo_u32 v3, v3, s75
	v_sub_u32_e32 v3, v38, v3
	v_add_u32_e32 v39, 0x600, v2
	v_add3_u32 v112, v3, s5, v18
	v_mul_hi_u32 v3, v39, s87
	v_lshrrev_b32_e32 v3, 6, v3
	v_mul_lo_u32 v20, v3, s86
	v_mul_lo_u32 v3, v3, s75
	v_sub_u32_e32 v3, v39, v3
	v_add_u32_e32 v40, 0x700, v2
	v_add3_u32 v114, v3, s5, v20
	v_mul_hi_u32 v3, v40, s87
	v_lshrrev_b32_e32 v3, 6, v3
	v_mul_lo_u32 v22, v3, s86
	v_mul_lo_u32 v3, v3, s75
	v_mov_b32_e32 v103, v179
	v_mov_b32_e32 v111, v179
	v_sub_u32_e32 v3, v40, v3
	v_lshl_add_u64 v[4:5], v[102:103], 1, s[12:13]
	v_mov_b32_e32 v105, v179
	v_mov_b32_e32 v107, v179
	v_mov_b32_e32 v109, v179
	v_lshl_add_u64 v[16:17], v[110:111], 1, s[12:13]
	v_mov_b32_e32 v113, v179
	v_mov_b32_e32 v115, v179
	v_add3_u32 v116, v3, s5, v22
	v_mov_b32_e32 v117, v179
	v_lshl_add_u64 v[6:7], v[104:105], 1, s[12:13]
	v_lshl_add_u64 v[12:13], v[106:107], 1, s[12:13]
	v_lshl_add_u64 v[14:15], v[108:109], 1, s[12:13]
	v_lshl_add_u64 v[18:19], v[112:113], 1, s[12:13]
	v_lshl_add_u64 v[20:21], v[114:115], 1, s[12:13]
	v_lshl_add_u64 v[22:23], v[116:117], 1, s[12:13]
	global_load_ushort v181, v[4:5], off
	global_load_ushort v182, v[6:7], off
	global_load_ushort v183, v[12:13], off
	global_load_ushort v184, v[14:15], off
	global_load_ushort v185, v[16:17], off
	global_load_ushort v186, v[18:19], off
	global_load_ushort v187, v[20:21], off
	global_load_ushort v188, v[22:23], off
	v_add_u32_e32 v16, 0x800, v2
	v_mul_hi_u32 v3, v16, s87
	v_lshrrev_b32_e32 v3, 6, v3
	v_mul_lo_u32 v4, v3, s86
	v_mul_lo_u32 v3, v3, s75
	v_sub_u32_e32 v3, v16, v3
	v_add_u32_e32 v17, 0x900, v2
	v_add3_u32 v118, v3, s5, v4
	v_mul_hi_u32 v3, v17, s87
	v_lshrrev_b32_e32 v3, 6, v3
	v_mul_lo_u32 v6, v3, s86
	v_mul_lo_u32 v3, v3, s75
	v_sub_u32_e32 v3, v17, v3
	v_add_u32_e32 v18, 0xa00, v2
	v_add3_u32 v120, v3, s5, v6
	v_mul_hi_u32 v3, v18, s87
	v_lshrrev_b32_e32 v3, 6, v3
	v_mul_lo_u32 v12, v3, s86
	v_mul_lo_u32 v3, v3, s75
	v_sub_u32_e32 v3, v18, v3
	v_add_u32_e32 v19, 0xb00, v2
	v_add3_u32 v122, v3, s5, v12
	v_mul_hi_u32 v3, v19, s87
	v_lshrrev_b32_e32 v3, 6, v3
	v_mul_lo_u32 v14, v3, s86
	v_mul_lo_u32 v3, v3, s75
	s_lshl_b64 s[10:11], s[54:55], 17
	s_lshl_b64 s[52:53], s[54:55], 11
	v_mov_b32_e32 v119, v179
	v_sub_u32_e32 v3, v19, v3
	v_lshl_add_u64 v[4:5], v[118:119], 1, s[12:13]
	v_mov_b32_e32 v121, v179
	v_mov_b32_e32 v123, v179
	v_add3_u32 v124, v3, s5, v14
	v_mov_b32_e32 v125, v179
	s_add_u32 s10, s56, s10
	v_ashrrev_i32_e32 v3, 31, v2
	v_lshl_add_u64 v[6:7], v[120:121], 1, s[12:13]
	v_lshl_add_u64 v[12:13], v[122:123], 1, s[12:13]
	v_lshl_add_u64 v[14:15], v[124:125], 1, s[12:13]
	global_load_ushort v189, v[4:5], off
	global_load_ushort v190, v[6:7], off
	global_load_ushort v191, v[12:13], off
	global_load_ushort v192, v[14:15], off
	s_addc_u32 s11, s57, s11
	v_lshlrev_b64 v[4:5], 2, v[2:3]
	v_add_u32_e32 v3, 47, v2
	v_lshl_add_u64 v[6:7], s[10:11], 0, v[4:5]
	v_lshlrev_b32_e32 v126, 2, v0
	v_cmp_gt_u32_e64 s[16:17], s67, v3
	v_and_b32_e32 v3, 0x7ffffff3, v0
	v_and_b32_e32 v1, 31, v2
	v_bfe_u32 v11, v2, 5, 1
	global_load_dword v193, v[6:7], off
	global_load_dword v194, v[6:7], off offset:1024
	v_and_b32_e32 v6, 16, v126
	v_lshlrev_b32_e32 v3, 1, v3
	v_and_b32_e32 v7, 8, v0
	v_ashrrev_i32_e32 v24, 6, v2
	s_movk_i32 s5, 0x8f
	v_or3_b32 v3, v6, v3, v7
	v_mul_u32_u24_e32 v6, 56, v1
	v_lshlrev_b32_e32 v128, 4, v11
	v_cmp_lt_i32_e64 s[14:15], s5, v2
	s_movk_i32 s5, 0x4c
	v_lshl_add_u32 v145, v6, 1, v128
	v_lshlrev_b32_e32 v6, 5, v24
	v_ashrrev_i32_e32 v9, 4, v9
	s_waitcnt vmcnt(30)
	v_mad_u64_u32 v[12:13], s[18:19], v0, s5, v[126:127]
	v_or_b32_e32 v7, v6, v1
	v_add_u32_e32 v9, v9, v10
	v_mad_u64_u32 v[130:131], s[18:19], v7, s74, v[128:129]
	v_lshlrev_b32_e32 v13, 5, v1
	v_mul_lo_u32 v10, v9, s75
	v_cmp_lt_i32_e64 s[10:11], 47, v2
	v_cmp_lt_i32_e64 s[12:13], s67, v2
	v_sub_u32_e32 v131, v145, v13
	v_sub_u32_e32 v2, v2, v10
	v_and_b32_e32 v10, 0x7ffffff3, v9
	v_lshlrev_b32_e32 v13, 2, v9
	v_mul_lo_u32 v2, v2, s74
	v_and_b32_e32 v13, 16, v13
	v_lshlrev_b32_e32 v10, 1, v10
	v_add3_u32 v2, v2, v13, v10
	v_and_or_b32 v146, v9, 8, v2
	v_mul_hi_i32 v2, v34, s79
	v_lshrrev_b32_e32 v9, 31, v2
	v_ashrrev_i32_e32 v2, 4, v2
	v_add_u32_e32 v2, v2, v9
	v_mul_lo_u32 v9, v2, s75
	v_sub_u32_e32 v9, v34, v9
	v_and_b32_e32 v10, 0x7ffffff3, v2
	v_lshlrev_b32_e32 v13, 2, v2
	v_mul_lo_u32 v9, v9, s74
	v_and_b32_e32 v13, 16, v13
	v_lshlrev_b32_e32 v10, 1, v10
	v_add3_u32 v9, v9, v13, v10
	v_and_or_b32 v148, v2, 8, v9
	v_mul_hi_i32 v2, v35, s79
	v_lshrrev_b32_e32 v9, 31, v2
	v_ashrrev_i32_e32 v2, 4, v2
	v_add_u32_e32 v2, v2, v9
	v_mul_lo_u32 v9, v2, s75
	v_sub_u32_e32 v9, v35, v9
	v_and_b32_e32 v10, 0x7ffffff3, v2
	v_lshlrev_b32_e32 v13, 2, v2
	v_mul_lo_u32 v9, v9, s74
	v_and_b32_e32 v13, 16, v13
	v_lshlrev_b32_e32 v10, 1, v10
	v_add3_u32 v9, v9, v13, v10
	v_and_or_b32 v149, v2, 8, v9
	v_mul_hi_i32 v2, v36, s79
	v_lshrrev_b32_e32 v9, 31, v2
	v_ashrrev_i32_e32 v2, 4, v2
	v_add_u32_e32 v2, v2, v9
	v_mul_lo_u32 v9, v2, s75
	v_sub_u32_e32 v9, v36, v9
	v_and_b32_e32 v10, 0x7ffffff3, v2
	v_lshlrev_b32_e32 v13, 2, v2
	v_mul_lo_u32 v9, v9, s74
	v_and_b32_e32 v13, 16, v13
	v_lshlrev_b32_e32 v10, 1, v10
	v_add3_u32 v9, v9, v13, v10
	v_and_or_b32 v150, v2, 8, v9
	v_mul_hi_i32 v2, v37, s79
	v_lshrrev_b32_e32 v9, 31, v2
	v_ashrrev_i32_e32 v2, 4, v2
	v_add_u32_e32 v2, v2, v9
	v_mul_lo_u32 v9, v2, s75
	v_sub_u32_e32 v9, v37, v9
	v_and_b32_e32 v10, 0x7ffffff3, v2
	v_lshlrev_b32_e32 v13, 2, v2
	v_mul_lo_u32 v9, v9, s74
	v_and_b32_e32 v13, 16, v13
	v_lshlrev_b32_e32 v10, 1, v10
	v_add3_u32 v9, v9, v13, v10
	v_and_or_b32 v151, v2, 8, v9
	v_mul_hi_i32 v2, v38, s79
	v_lshrrev_b32_e32 v9, 31, v2
	v_ashrrev_i32_e32 v2, 4, v2
	v_add_u32_e32 v2, v2, v9
	v_mul_lo_u32 v9, v2, s75
	v_sub_u32_e32 v9, v38, v9
	v_and_b32_e32 v10, 0x7ffffff3, v2
	v_lshlrev_b32_e32 v13, 2, v2
	v_mul_lo_u32 v9, v9, s74
	v_and_b32_e32 v13, 16, v13
	v_lshlrev_b32_e32 v10, 1, v10
	v_add3_u32 v9, v9, v13, v10
	v_and_or_b32 v152, v2, 8, v9
	v_mul_hi_i32 v2, v39, s79
	v_lshrrev_b32_e32 v9, 31, v2
	v_ashrrev_i32_e32 v2, 4, v2
	v_add_u32_e32 v2, v2, v9
	v_mul_lo_u32 v9, v2, s75
	v_sub_u32_e32 v9, v39, v9
	v_and_b32_e32 v10, 0x7ffffff3, v2
	v_lshlrev_b32_e32 v13, 2, v2
	v_mul_lo_u32 v9, v9, s74
	v_and_b32_e32 v13, 16, v13
	v_lshlrev_b32_e32 v10, 1, v10
	v_add3_u32 v9, v9, v13, v10
	v_and_or_b32 v153, v2, 8, v9
	v_mul_hi_i32 v2, v40, s79
	v_lshrrev_b32_e32 v9, 31, v2
	v_ashrrev_i32_e32 v2, 4, v2
	v_add_u32_e32 v2, v2, v9
	v_mul_lo_u32 v9, v2, s75
	v_sub_u32_e32 v9, v40, v9
	v_and_b32_e32 v10, 0x7ffffff3, v2
	v_lshlrev_b32_e32 v13, 2, v2
	v_mul_lo_u32 v9, v9, s74
	v_and_b32_e32 v13, 16, v13
	v_lshlrev_b32_e32 v10, 1, v10
	v_add3_u32 v9, v9, v13, v10
	v_and_or_b32 v154, v2, 8, v9
	v_mul_hi_i32 v2, v16, s79
	v_lshrrev_b32_e32 v9, 31, v2
	v_ashrrev_i32_e32 v2, 4, v2
	v_add_u32_e32 v2, v2, v9
	v_mul_lo_u32 v9, v2, s75
	v_sub_u32_e32 v9, v16, v9
	v_and_b32_e32 v10, 0x7ffffff3, v2
	v_lshlrev_b32_e32 v13, 2, v2
	v_mul_lo_u32 v9, v9, s74
	v_and_b32_e32 v13, 16, v13
	v_lshlrev_b32_e32 v10, 1, v10
	v_add3_u32 v9, v9, v13, v10
	v_and_or_b32 v155, v2, 8, v9
	v_mul_hi_i32 v2, v17, s79
	v_lshrrev_b32_e32 v9, 31, v2
	v_ashrrev_i32_e32 v2, 4, v2
	v_add_u32_e32 v2, v2, v9
	v_mul_lo_u32 v9, v2, s75
	v_sub_u32_e32 v9, v17, v9
	v_and_b32_e32 v10, 0x7ffffff3, v2
	v_lshlrev_b32_e32 v13, 2, v2
	v_mul_lo_u32 v9, v9, s74
	v_and_b32_e32 v13, 16, v13
	v_lshlrev_b32_e32 v10, 1, v10
	v_add3_u32 v9, v9, v13, v10
	v_and_or_b32 v156, v2, 8, v9
	v_mul_hi_i32 v2, v18, s79
	v_lshrrev_b32_e32 v9, 31, v2
	v_ashrrev_i32_e32 v2, 4, v2
	v_add_u32_e32 v2, v2, v9
	v_mul_lo_u32 v9, v2, s75
	v_sub_u32_e32 v9, v18, v9
	v_and_b32_e32 v10, 0x7ffffff3, v2
	v_lshlrev_b32_e32 v13, 2, v2
	v_mul_lo_u32 v9, v9, s74
	v_and_b32_e32 v13, 16, v13
	v_lshlrev_b32_e32 v10, 1, v10
	v_add3_u32 v9, v9, v13, v10
	v_and_or_b32 v157, v2, 8, v9
	v_mul_hi_i32 v2, v19, s79
	v_lshrrev_b32_e32 v9, 31, v2
	v_ashrrev_i32_e32 v2, 4, v2
	v_add_u32_e32 v2, v2, v9
	v_mul_lo_u32 v9, v2, s75
	v_sub_u32_e32 v9, v19, v9
	v_and_b32_e32 v10, 0x7ffffff3, v2
	v_lshlrev_b32_e32 v13, 2, v2
	v_mul_lo_u32 v9, v9, s74
	v_and_b32_e32 v13, 16, v13
	v_lshlrev_b32_e32 v10, 1, v10
	v_add3_u32 v9, v9, v13, v10
	s_movk_i32 s5, 0x1c0
	v_and_or_b32 v158, v2, 8, v9
	v_mul_lo_u32 v2, v8, s5
	v_add_lshl_u32 v159, v2, v0, 1
	v_lshl_add_u32 v160, v2, 1, v3
	v_lshlrev_b32_e32 v2, 4, v8
	v_lshlrev_b32_e32 v141, 9, v8
	v_and_b32_e32 v2, 0xffffffe0, v2
	v_and_b32_e32 v8, 8, v25
	s_mov_b32 s5, 0x7ffffff1
	v_add3_u32 v161, v12, v2, v8
	v_or_b32_e32 v2, 1, v25
	v_bitop3_b32 v9, v25, s5, 1 bitop3:0xc8
	v_mul_lo_u32 v2, v2, 56
	v_lshlrev_b32_e32 v9, 1, v9
	v_add3_u32 v164, v12, v9, v8
	v_add_u32_e32 v9, 56, v2
	s_mov_b32 s5, 0x7ffffff2
	v_add_lshl_u32 v165, v9, v0, 1
	v_lshl_add_u32 v166, v9, 1, v3
	v_bitop3_b32 v9, v25, s5, 2 bitop3:0xc8
	v_lshlrev_b32_e32 v9, 1, v9
	v_add3_u32 v167, v12, v9, v8
	v_add_u32_e32 v9, 0x70, v2
	s_mov_b32 s5, 0x7ffffff3
	v_add_lshl_u32 v168, v9, v0, 1
	v_lshl_add_u32 v169, v9, 1, v3
	v_bitop3_b32 v9, v25, s5, 3 bitop3:0xc8
	v_lshlrev_b32_e32 v9, 1, v9
	v_add3_u32 v170, v12, v9, v8
	v_add_u32_e32 v8, 0xe0, v2
	v_lshlrev_b32_e32 v11, 2, v11
	v_add_lshl_u32 v162, v2, v0, 1
	v_lshl_add_u32 v163, v2, 1, v3
	v_add_lshl_u32 v171, v8, v0, 1
	v_lshl_add_u32 v172, v8, 1, v3
	v_add_u32_e32 v8, 0x118, v2
	v_add_u32_e32 v2, 0x150, v2
	v_add_lshl_u32 v173, v8, v0, 1
	v_add_lshl_u32 v175, v2, v0, 1
	v_or_b32_e32 v0, 2, v11
	v_cmp_gt_u32_e64 s[22:23], v0, v1
	v_or_b32_e32 v0, 3, v11
	v_cmp_gt_u32_e64 s[24:25], v0, v1
	v_or_b32_e32 v0, 8, v11
	v_cmp_gt_u32_e64 s[26:27], v0, v1
	v_or_b32_e32 v0, 9, v11
	v_cmp_gt_u32_e64 s[28:29], v0, v1
	v_or_b32_e32 v0, 10, v11
	v_cmp_gt_u32_e64 s[30:31], v0, v1
	v_or_b32_e32 v0, 11, v11
	v_cmp_gt_u32_e64 s[34:35], v0, v1
	v_or_b32_e32 v0, 16, v11
	v_cmp_gt_u32_e64 s[36:37], v0, v1
	v_or_b32_e32 v0, 17, v11
	v_cmp_gt_u32_e64 s[38:39], v0, v1
	v_or_b32_e32 v0, 18, v11
	v_cmp_gt_u32_e64 s[40:41], v0, v1
	v_or_b32_e32 v0, 19, v11
	v_cmp_gt_u32_e64 s[42:43], v0, v1
	v_or_b32_e32 v0, 24, v11
	v_cmp_gt_u32_e64 s[44:45], v0, v1
	v_or_b32_e32 v0, 25, v11
	v_cmp_gt_u32_e64 s[46:47], v0, v1
	v_or_b32_e32 v0, 26, v11
	v_cmp_gt_u32_e64 s[48:49], v0, v1
	v_or_b32_e32 v0, 27, v11
	v_lshl_add_u32 v180, v2, 1, v3
	v_cmp_gt_u32_e64 s[50:51], v0, v1
	s_mul_hi_i32 s5, s54, 0x300000
	s_mul_i32 s54, s54, 0x300000
	v_mul_hi_u32_u24_e32 v0, 0x600, v1
	v_mul_u32_u24_e32 v2, 0x600, v1
	v_cmp_gt_u32_e64 s[18:19], v11, v1
	v_cmp_lt_u32_e64 s[20:21], v11, v1
	v_or_b32_e32 v1, s5, v0
	v_or_b32_e32 v0, s54, v2
	v_mad_u64_u32 v[0:1], s[4:5], s4, v231, v[0:1]
	v_ashrrev_i32_e32 v7, 31, v6
	v_or_b32_e32 v0, v0, v128
	v_lshl_add_u64 v[0:1], v[6:7], 2, v[0:1]
	v_lshl_add_u64 v[0:1], s[2:3], 0, v[0:1]
	s_mov_b64 s[2:3], 0x26e22140
	v_mov_b32_e32 v14, v179
	v_mov_b32_e32 v15, v179
	v_cmp_gt_i32_e32 vcc, 3, v24
	v_lshl_add_u32 v174, v8, 1, v3
	s_waitcnt vmcnt(27)
	v_perm_b32 v39, v27, v26, s76
	s_waitcnt vmcnt(23)
	v_perm_b32 v38, v29, v28, s76
	s_waitcnt vmcnt(19)
	v_perm_b32 v37, v31, v30, s76
	v_lshl_add_u64 v[132:133], s[56:57], 0, v[4:5]
	v_lshl_add_u64 v[134:135], v[0:1], 0, s[2:3]
	v_mov_b32_e32 v0, v179
	v_mov_b32_e32 v1, v179
	v_mov_b32_e32 v2, v179
	v_mov_b32_e32 v3, v179
	v_mov_b32_e32 v4, v179
	v_mov_b32_e32 v5, v179
	v_mov_b32_e32 v6, v179
	v_mov_b32_e32 v7, v179
	v_mov_b32_e32 v8, v179
	v_mov_b32_e32 v9, v179
	v_mov_b32_e32 v10, v179
	v_mov_b32_e32 v11, v179
	v_mov_b32_e32 v12, v179
	v_mov_b32_e32 v13, v179
	v_mov_b64_e32 v[30:31], v[14:15]
	s_waitcnt vmcnt(15)
	v_perm_b32 v36, v33, v32, s76
	s_mov_b32 s56, 32
	v_mov_b64_e32 v[28:29], v[12:13]
	v_mov_b64_e32 v[26:27], v[10:11]
	v_mov_b64_e32 v[24:25], v[8:9]
	v_mov_b64_e32 v[22:23], v[6:7]
	v_mov_b64_e32 v[20:21], v[4:5]
	v_mov_b64_e32 v[18:19], v[2:3]
	v_mov_b64_e32 v[16:17], v[0:1]
	v_lshlrev_b32_e32 v72, 1, v72
	v_lshlrev_b32_e32 v73, 1, v74
	v_lshlrev_b32_e32 v74, 1, v76
	v_lshlrev_b32_e32 v75, 1, v78
	v_lshlrev_b32_e32 v76, 1, v80
	v_lshlrev_b32_e32 v77, 1, v82
	v_lshlrev_b32_e32 v78, 1, v84
	v_lshlrev_b32_e32 v79, 1, v86
	v_lshlrev_b32_e32 v80, 1, v88
	v_lshlrev_b32_e32 v81, 1, v90
	v_lshlrev_b32_e32 v82, 1, v92
	v_lshlrev_b32_e32 v83, 1, v94
	v_lshlrev_b32_e32 v84, 1, v96
	v_lshlrev_b32_e32 v85, 1, v98
	v_lshlrev_b32_e32 v86, 1, v100
	v_lshlrev_b32_e32 v87, 1, v102
	v_lshlrev_b32_e32 v88, 1, v104
	v_lshlrev_b32_e32 v89, 1, v106
	v_lshlrev_b32_e32 v90, 1, v108
	v_lshlrev_b32_e32 v91, 1, v110
	v_lshlrev_b32_e32 v92, 1, v112
	v_lshlrev_b32_e32 v93, 1, v114
	v_lshlrev_b32_e32 v94, 1, v116
	v_lshlrev_b32_e32 v95, 1, v118
	v_lshlrev_b32_e32 v96, 1, v120
	v_lshlrev_b32_e32 v97, 1, v122
	v_lshlrev_b32_e32 v98, 1, v124
	s_branch .LBB0_537

.LBB0_543:
	s_or_b64 exec, exec, s[2:3]
	s_cmpk_lg_i32 s56, 0x800
	s_cselect_b32 s2, s56, 0x7e0
	s_add_u32 s2, s52, s2
	s_addc_u32 s3, s53, 0
	s_mul_i32 s4, s3, 0x900
	s_mul_hi_u32 s5, s2, 0x900
	s_add_i32 s5, s5, s4
	s_mul_i32 s4, s2, 0x900
	s_add_u32 s54, s58, s4
	s_addc_u32 s55, s59, s5
	v_lshl_add_u64 v[32:33], v[178:179], 1, s[54:55]
	s_waitcnt lgkmcnt(0)
	s_barrier
	global_load_ushort v195, v[32:33], off
	global_load_ushort v143, v72, s[54:55]
	global_load_ushort v196, v73, s[54:55]
	global_load_ushort v140, v74, s[54:55]
	global_load_ushort v197, v75, s[54:55]
	global_load_ushort v136, v76, s[54:55]
	global_load_ushort v198, v77, s[54:55]
	global_load_ushort v138, v78, s[54:55]
	global_load_ushort v199, v79, s[54:55]
	global_load_ushort v144, v80, s[54:55]
	global_load_ushort v200, v81, s[54:55]
	global_load_ushort v142, v82, s[54:55]
	global_load_ushort v201, v83, s[54:55]
	global_load_ushort v137, v84, s[54:55]
	global_load_ushort v202, v85, s[54:55]
	global_load_ushort v139, v86, s[54:55]
	global_load_ushort v181, v87, s[54:55]
	global_load_ushort v182, v88, s[54:55]
	global_load_ushort v183, v89, s[54:55]
	global_load_ushort v184, v90, s[54:55]
	global_load_ushort v185, v91, s[54:55]
	global_load_ushort v186, v92, s[54:55]
	global_load_ushort v187, v93, s[54:55]
	global_load_ushort v188, v94, s[54:55]
	global_load_ushort v189, v95, s[54:55]
	global_load_ushort v190, v96, s[54:55]
	s_lshl_b64 s[2:3], s[2:3], 6
	global_load_ushort v191, v97, s[54:55]
	global_load_ushort v192, v98, s[54:55]
	v_lshl_add_u64 v[32:33], v[132:133], 0, s[2:3]
	global_load_dword v193, v[32:33], off
	global_load_dword v194, v[32:33], off offset:1024
	s_and_saveexec_b64 s[2:3], vcc
	s_cbranch_execz .LBB0_536
	ds_read_b128 v[100:103], v145 offset:7168
	ds_read_b128 v[104:107], v145
	ds_read_b128 v[108:111], v145 offset:7200
	ds_read_b128 v[112:115], v145 offset:32
	ds_read_b128 v[116:119], v145 offset:7232
	ds_read_b128 v[120:123], v145 offset:64
	ds_read_b128 v[52:55], v130 offset:15872
	ds_read_b128 v[48:51], v130 offset:15904
	ds_read_b128 v[240:243], v128 offset:23552
	ds_read_b128 v[244:247], v128 offset:23584
	ds_read_b128 v[248:251], v128 offset:23616
	ds_read_b128 v[236:239], v128 offset:23648
	v_cvt_pk_bf16_f32 v204, v0, v1
	v_cvt_pk_bf16_f32 v205, v2, v3
	v_cvt_pk_bf16_f32 v206, v4, v5
	v_cvt_pk_bf16_f32 v207, v6, v7
	v_cvt_pk_bf16_f32 v208, v8, v9
	v_cvt_pk_bf16_f32 v209, v10, v11
	v_cvt_pk_bf16_f32 v210, v12, v13
	v_cvt_pk_bf16_f32 v211, v14, v15
	v_cvt_pk_bf16_f32 v212, v16, v17
	v_cvt_pk_bf16_f32 v213, v18, v19
	v_cvt_pk_bf16_f32 v214, v20, v21
	v_cvt_pk_bf16_f32 v215, v22, v23
	s_waitcnt lgkmcnt(10)
	v_mfma_f32_32x32x16_bf16 v[32:47], v[100:103], v[104:107], 0
	s_waitcnt lgkmcnt(8)
	v_mfma_f32_32x32x16_bf16 v[32:47], v[108:111], v[112:115], v[32:47]
	s_waitcnt lgkmcnt(6)
	v_mfma_f32_32x32x16_bf16 v[32:47], v[116:119], v[120:123], v[32:47]
	ds_read_b128 v[100:103], v128 offset:23680
	ds_read_b128 v[104:107], v128 offset:23712
	ds_read_b128 v[108:111], v128 offset:23744
	ds_read_b128 v[112:115], v128 offset:23776
	ds_read_b128 v[116:119], v131 offset:10752
	ds_read_b128 v[120:123], v131 offset:10784
	s_waitcnt lgkmcnt(6)
	v_pk_mul_f32 v[0:1], v[0:1], v[240:241]
	v_pk_mul_f32 v[2:3], v[2:3], v[242:243]
	v_pk_mul_f32 v[4:5], v[4:5], v[244:245]
	v_pk_mul_f32 v[6:7], v[6:7], v[246:247]
	v_pk_mul_f32 v[8:9], v[8:9], v[248:249]
	v_pk_mul_f32 v[10:11], v[10:11], v[250:251]
	v_pk_mul_f32 v[12:13], v[12:13], v[236:237]
	v_pk_mul_f32 v[14:15], v[14:15], v[238:239]
	ds_read_b128 v[240:243], v131 offset:13312
	ds_read_b128 v[244:247], v131 offset:13344
	ds_read_b128 v[248:251], v145 offset:3584
	ds_read_b128 v[236:239], v145 offset:3616
	s_waitcnt lgkmcnt(5)
	s_nop 0
	v_mfma_f32_32x32x16_bf16 v[0:15], v[116:119], v[52:55], v[0:15]
	v_pk_mul_f32 v[16:17], v[16:17], v[100:101]
	v_pk_mul_f32 v[18:19], v[18:19], v[102:103]
	v_pk_mul_f32 v[20:21], v[20:21], v[104:105]
	v_pk_mul_f32 v[22:23], v[22:23], v[106:107]
	v_pk_mul_f32 v[24:25], v[24:25], v[108:109]
	v_pk_mul_f32 v[26:27], v[26:27], v[110:111]
	v_pk_mul_f32 v[28:29], v[28:29], v[112:113]
	v_pk_mul_f32 v[30:31], v[30:31], v[114:115]
	ds_read_b128 v[100:103], v145 offset:3648
	s_waitcnt lgkmcnt(3)
	s_nop 0
	v_mfma_f32_32x32x16_bf16 v[16:31], v[240:243], v[52:55], v[16:31]
	v_mfma_f32_32x32x16_bf16 v[0:15], v[120:123], v[48:51], v[0:15]
	v_mfma_f32_32x32x16_bf16 v[16:31], v[244:247], v[48:51], v[16:31]
	s_nop 7
	v_cndmask_b32_e64 v32, v32, 0, s[18:19]
	v_cndmask_b32_e64 v33, 0, v33, s[20:21]
	v_cndmask_b32_e64 v34, v34, 0, s[22:23]
	v_cndmask_b32_e64 v35, v35, 0, s[24:25]
	v_cndmask_b32_e64 v36, v36, 0, s[26:27]
	v_cndmask_b32_e64 v37, v37, 0, s[28:29]
	v_cndmask_b32_e64 v38, v38, 0, s[30:31]
	v_cndmask_b32_e64 v39, v39, 0, s[34:35]
	v_cndmask_b32_e64 v40, v40, 0, s[36:37]
	v_cndmask_b32_e64 v41, v41, 0, s[38:39]
	v_cndmask_b32_e64 v42, v42, 0, s[40:41]
	v_cndmask_b32_e64 v43, v43, 0, s[42:43]
	v_cndmask_b32_e64 v44, v44, 0, s[44:45]
	v_cndmask_b32_e64 v45, v45, 0, s[46:47]
	v_cndmask_b32_e64 v46, v46, 0, s[48:49]
	v_cndmask_b32_e64 v47, v47, 0, s[50:51]
	v_cvt_pk_bf16_f32 v32, v32, v33
	v_cvt_pk_bf16_f32 v33, v34, v35
	v_cvt_pk_bf16_f32 v34, v36, v37
	v_cvt_pk_bf16_f32 v35, v38, v39
	v_cvt_pk_bf16_f32 v104, v40, v41
	v_cvt_pk_bf16_f32 v105, v42, v43
	v_cvt_pk_bf16_f32 v106, v44, v45
	v_cvt_pk_bf16_f32 v107, v46, v47
	s_nop 1
	v_mfma_f32_32x32x16_bf16 v[32:47], v[52:55], v[32:35], 0
	v_mfma_f32_32x32x16_bf16 v[32:47], v[48:51], v[104:107], v[32:47]
	s_waitcnt lgkmcnt(0)
	v_mfma_f32_32x32x16_bf16 v[32:47], v[204:207], v[248:251], v[32:47]
	v_mfma_f32_32x32x16_bf16 v[32:47], v[208:211], v[236:239], v[32:47]
	v_mfma_f32_32x32x16_bf16 v[32:47], v[212:215], v[100:103], v[32:47]
	s_nop 15
	global_store_dwordx4 v[134:135], v[32:35], off offset:-64
	global_store_dwordx4 v[134:135], v[36:39], off offset:-32
	global_store_dwordx4 v[134:135], v[40:43], off
	global_store_dwordx4 v[134:135], v[44:47], off offset:32
	s_branch .LBB0_536
